# residual epilogue: second-half residual loads issued after the first-half block whose registers they reuse, ahead of the later first-half stores; counted waits instead of waiting for those stores
# speedup vs baseline: 1.0127x; 1.0127x over previous
; __device__ __forceinline__ u32x4 pack8(const f32x4& v0, const f32x4& v1) { u32x4 w; w.x = cvt_pk_bf16(v0[0], v0[1]); w.y = cvt_pk_bf16(v0[2], v0[3]); w.z = cvt_pk_bf16(v1[0], v1[1]); w.w = cvt_pk_bf16(v1[2], v1[3]); return w; }
;     __device__ __forceinline__ void operator()(const f32x4 (&acc)[2][2][4][2], const Unit& u, int wr, int wc, int fr, int fq) const {
;     ...
;             f32x4 bpre[4][2][2];
; #pragma unroll
;             for (int m = 0; m < 4; ++m)
; #pragma unroll
;                 for (int bj = 0; bj < 2; ++bj) { const float* bp = base + (size_t)(row0 + ai * HALF + m * 16) * 1024 + col0 + bj * HALF; bpre[m][bj][0] = *(const f32x4*)bp; bpre[m][bj][1] = *(const f32x4*)(bp + 4); }
; #pragma unroll
;             for (int m = 0; m < 4; ++m) { const int row = row0 + ai * HALF + m * 16; const size_t off = (size_t)row * 1024 + col0; float ss = 0.f;
; #pragma unroll
;                 for (int bj = 0; bj < 2; ++bj) { float* op = out + off + bj * HALF;
;                     const f32x4 x0 = bpre[m][bj][0] + acc[ai][bj][m][0], x1 = bpre[m][bj][1] + acc[ai][bj][m][1];
;                     *(f32x4*)op = x0; *(f32x4*)(op + 4) = x1;
;                     if (XG) { ss += ((x0[0] * x0[0] + x0[1] * x0[1]) + (x0[2] * x0[2] + x0[3] * x0[3])) + ((x1[0] * x1[0] + x1[1] * x1[1]) + (x1[2] * x1[2] + x1[3] * x1[3]));
;                         *(u32x4*)(XG + off + bj * HALF) = pack8(x0 * g0[bj], x1 * g1[bj]); } }
.LBB0_73:
	v_add_u32_e32 v142, 0x80, v232
	v_ashrrev_i32_e32 v143, 31, v142
	v_lshlrev_b64 v[142:143], 12, v[142:143]
	v_lshl_add_u64 v[142:143], v[230:231], 0, v[142:143]
	global_load_dwordx4 v[200:203], v[142:143], off offset:16
	global_load_dwordx4 v[204:207], v[142:143], off
	global_load_dwordx4 v[192:195], v[142:143], off offset:528
	global_load_dwordx4 v[196:199], v[142:143], off offset:512
	s_waitcnt lgkmcnt(0)
	v_lshlrev_b64 v[128:129], 10, v[238:239]
	v_lshl_add_u64 v[138:139], v[128:129], 0, v[228:229]
	v_lshl_add_u64 v[136:137], v[138:139], 2, s[20:21]
	v_pk_add_f32 v[130:131], v[126:127], v[190:191]
	v_pk_add_f32 v[128:129], v[124:125], v[188:189]
	v_pk_add_f32 v[134:135], v[122:123], v[186:187]
	v_pk_add_f32 v[132:133], v[120:121], v[184:185]
	s_mov_b64 s[58:59], -1
	s_and_b64 vcc, exec, s[52:53]
	v_pk_add_f32 v[124:125], v[116:117], v[180:181]
	v_pk_add_f32 v[120:121], v[112:113], v[176:177]
	global_store_dwordx4 v[136:137], v[128:131], off
	global_store_dwordx4 v[136:137], v[132:135], off offset:16
	s_cbranch_vccz .LBB0_75
	v_pk_add_f32 v[126:127], v[118:119], v[182:183]
	v_pk_add_f32 v[122:123], v[114:115], v[178:179]
	global_store_dwordx4 v[136:137], v[124:127], off offset:512
	global_store_dwordx4 v[136:137], v[120:123], off offset:528
	s_mov_b64 s[58:59], 0

; __device__ __forceinline__ u32x4 pack8(const f32x4& v0, const f32x4& v1) { u32x4 w; w.x = cvt_pk_bf16(v0[0], v0[1]); w.y = cvt_pk_bf16(v0[2], v0[3]); w.z = cvt_pk_bf16(v1[0], v1[1]); w.w = cvt_pk_bf16(v1[2], v1[3]); return w; }
;     __device__ __forceinline__ void operator()(const f32x4 (&acc)[2][2][4][2], const Unit& u, int wr, int wc, int fr, int fq) const {
;     ...
;             f32x4 bpre[4][2][2];
; #pragma unroll
;             for (int m = 0; m < 4; ++m)
; #pragma unroll
;                 for (int bj = 0; bj < 2; ++bj) { const float* bp = base + (size_t)(row0 + ai * HALF + m * 16) * 1024 + col0 + bj * HALF; bpre[m][bj][0] = *(const f32x4*)bp; bpre[m][bj][1] = *(const f32x4*)(bp + 4); }
; #pragma unroll
;             for (int m = 0; m < 4; ++m) { const int row = row0 + ai * HALF + m * 16; const size_t off = (size_t)row * 1024 + col0; float ss = 0.f;
; #pragma unroll
;                 for (int bj = 0; bj < 2; ++bj) { float* op = out + off + bj * HALF;
;                     const f32x4 x0 = bpre[m][bj][0] + acc[ai][bj][m][0], x1 = bpre[m][bj][1] + acc[ai][bj][m][1];
;                     *(f32x4*)op = x0; *(f32x4*)(op + 4) = x1;
;                     if (XG) { ss += ((x0[0] * x0[0] + x0[1] * x0[1]) + (x0[2] * x0[2] + x0[3] * x0[3])) + ((x1[0] * x1[0] + x1[1] * x1[1]) + (x1[2] * x1[2] + x1[3] * x1[3]));
;                         *(u32x4*)(XG + off + bj * HALF) = pack8(x0 * g0[bj], x1 * g1[bj]); } }
.LBB0_79:
	v_add_u32_e32 v142, 0x90, v232
	v_ashrrev_i32_e32 v143, 31, v142
	v_lshlrev_b64 v[142:143], 12, v[142:143]
	v_lshl_add_u64 v[142:143], v[230:231], 0, v[142:143]
	global_load_dwordx4 v[184:187], v[142:143], off offset:16
	global_load_dwordx4 v[188:191], v[142:143], off
	global_load_dwordx4 v[176:179], v[142:143], off offset:528
	global_load_dwordx4 v[180:183], v[142:143], off offset:512
	s_waitcnt lgkmcnt(0)
	v_lshlrev_b64 v[112:113], 10, v[236:237]
	v_lshl_add_u64 v[122:123], v[112:113], 0, v[228:229]
	v_lshl_add_u64 v[120:121], v[122:123], 2, s[20:21]
	v_pk_add_f32 v[114:115], v[110:111], v[174:175]
	v_pk_add_f32 v[112:113], v[108:109], v[172:173]
	v_pk_add_f32 v[118:119], v[106:107], v[170:171]
	v_pk_add_f32 v[116:117], v[104:105], v[168:169]
	s_mov_b64 s[58:59], -1
	s_and_b64 vcc, exec, s[52:53]
	v_pk_add_f32 v[108:109], v[100:101], v[164:165]
	v_pk_add_f32 v[104:105], v[96:97], v[160:161]
	global_store_dwordx4 v[120:121], v[112:115], off
	global_store_dwordx4 v[120:121], v[116:119], off offset:16
	s_cbranch_vccz .LBB0_81
	v_pk_add_f32 v[110:111], v[102:103], v[166:167]
	v_pk_add_f32 v[106:107], v[98:99], v[162:163]
	global_store_dwordx4 v[120:121], v[108:111], off offset:512
	global_store_dwordx4 v[120:121], v[104:107], off offset:528
	s_mov_b64 s[58:59], 0

; __device__ __forceinline__ u32x4 pack8(const f32x4& v0, const f32x4& v1) { u32x4 w; w.x = cvt_pk_bf16(v0[0], v0[1]); w.y = cvt_pk_bf16(v0[2], v0[3]); w.z = cvt_pk_bf16(v1[0], v1[1]); w.w = cvt_pk_bf16(v1[2], v1[3]); return w; }
;     __device__ __forceinline__ void operator()(const f32x4 (&acc)[2][2][4][2], const Unit& u, int wr, int wc, int fr, int fq) const {
;     ...
;             f32x4 bpre[4][2][2];
; #pragma unroll
;             for (int m = 0; m < 4; ++m)
; #pragma unroll
;                 for (int bj = 0; bj < 2; ++bj) { const float* bp = base + (size_t)(row0 + ai * HALF + m * 16) * 1024 + col0 + bj * HALF; bpre[m][bj][0] = *(const f32x4*)bp; bpre[m][bj][1] = *(const f32x4*)(bp + 4); }
; #pragma unroll
;             for (int m = 0; m < 4; ++m) { const int row = row0 + ai * HALF + m * 16; const size_t off = (size_t)row * 1024 + col0; float ss = 0.f;
; #pragma unroll
;                 for (int bj = 0; bj < 2; ++bj) { float* op = out + off + bj * HALF;
;                     const f32x4 x0 = bpre[m][bj][0] + acc[ai][bj][m][0], x1 = bpre[m][bj][1] + acc[ai][bj][m][1];
;                     *(f32x4*)op = x0; *(f32x4*)(op + 4) = x1;
;                     if (XG) { ss += ((x0[0] * x0[0] + x0[1] * x0[1]) + (x0[2] * x0[2] + x0[3] * x0[3])) + ((x1[0] * x1[0] + x1[1] * x1[1]) + (x1[2] * x1[2] + x1[3] * x1[3]));
;                         *(u32x4*)(XG + off + bj * HALF) = pack8(x0 * g0[bj], x1 * g1[bj]); } }
.LBB0_85:
	v_add_u32_e32 v142, 0xa0, v232
	v_ashrrev_i32_e32 v143, 31, v142
	v_lshlrev_b64 v[142:143], 12, v[142:143]
	v_lshl_add_u64 v[142:143], v[230:231], 0, v[142:143]
	global_load_dwordx4 v[168:171], v[142:143], off offset:16
	global_load_dwordx4 v[172:175], v[142:143], off
	global_load_dwordx4 v[160:163], v[142:143], off offset:528
	global_load_dwordx4 v[164:167], v[142:143], off offset:512
	s_waitcnt lgkmcnt(0)
	v_lshlrev_b64 v[96:97], 10, v[234:235]
	v_lshl_add_u64 v[106:107], v[96:97], 0, v[228:229]
	v_lshl_add_u64 v[104:105], v[106:107], 2, s[20:21]
	v_pk_add_f32 v[98:99], v[94:95], v[158:159]
	v_pk_add_f32 v[96:97], v[92:93], v[156:157]
	v_pk_add_f32 v[102:103], v[90:91], v[154:155]
	v_pk_add_f32 v[100:101], v[88:89], v[152:153]
	s_mov_b64 s[58:59], -1
	s_and_b64 vcc, exec, s[52:53]
	v_pk_add_f32 v[92:93], v[84:85], v[148:149]
	v_pk_add_f32 v[88:89], v[80:81], v[144:145]
	global_store_dwordx4 v[104:105], v[96:99], off
	global_store_dwordx4 v[104:105], v[100:103], off offset:16
	s_cbranch_vccz .LBB0_87
	v_pk_add_f32 v[94:95], v[86:87], v[150:151]
	v_pk_add_f32 v[90:91], v[82:83], v[146:147]
	global_store_dwordx4 v[104:105], v[92:95], off offset:512
	global_store_dwordx4 v[104:105], v[88:91], off offset:528
	s_mov_b64 s[58:59], 0

; __device__ __forceinline__ u32x4 pack8(const f32x4& v0, const f32x4& v1) { u32x4 w; w.x = cvt_pk_bf16(v0[0], v0[1]); w.y = cvt_pk_bf16(v0[2], v0[3]); w.z = cvt_pk_bf16(v1[0], v1[1]); w.w = cvt_pk_bf16(v1[2], v1[3]); return w; }
;     __device__ __forceinline__ void operator()(const f32x4 (&acc)[2][2][4][2], const Unit& u, int wr, int wc, int fr, int fq) const {
;     ...
;             f32x4 bpre[4][2][2];
; #pragma unroll
;             for (int m = 0; m < 4; ++m)
; #pragma unroll
;                 for (int bj = 0; bj < 2; ++bj) { const float* bp = base + (size_t)(row0 + ai * HALF + m * 16) * 1024 + col0 + bj * HALF; bpre[m][bj][0] = *(const f32x4*)bp; bpre[m][bj][1] = *(const f32x4*)(bp + 4); }
; #pragma unroll
;             for (int m = 0; m < 4; ++m) { const int row = row0 + ai * HALF + m * 16; const size_t off = (size_t)row * 1024 + col0; float ss = 0.f;
; #pragma unroll
;                 for (int bj = 0; bj < 2; ++bj) { float* op = out + off + bj * HALF;
;                     const f32x4 x0 = bpre[m][bj][0] + acc[ai][bj][m][0], x1 = bpre[m][bj][1] + acc[ai][bj][m][1];
;                     *(f32x4*)op = x0; *(f32x4*)(op + 4) = x1;
;                     if (XG) { ss += ((x0[0] * x0[0] + x0[1] * x0[1]) + (x0[2] * x0[2] + x0[3] * x0[3])) + ((x1[0] * x1[0] + x1[1] * x1[1]) + (x1[2] * x1[2] + x1[3] * x1[3]));
;                         *(u32x4*)(XG + off + bj * HALF) = pack8(x0 * g0[bj], x1 * g1[bj]); } }
;                 if (XG) { ss += __shfl_xor(ss, 16); ss += __shfl_xor(ss, 32); if (fq == 0) rss[(size_t)row * 16 + u.pn * 4 + wc] = ss; } }
.LBB0_91:
	v_add_u32_e32 v86, 0x80, v232
	v_ashrrev_i32_e32 v87, 31, v86
	s_waitcnt lgkmcnt(0)
	v_lshlrev_b64 v[144:145], 12, v[86:87]
	v_add_u32_e32 v84, 0x90, v232
	v_lshl_add_u64 v[144:145], v[230:231], 0, v[144:145]
	v_ashrrev_i32_e32 v85, 31, v84
	v_lshlrev_b64 v[144:145], 12, v[84:85]
	v_add_u32_e32 v82, 0xa0, v232
	v_lshl_add_u64 v[144:145], v[230:231], 0, v[144:145]
	v_ashrrev_i32_e32 v83, 31, v82
	v_lshlrev_b64 v[144:145], 12, v[82:83]
	v_add_u32_e32 v80, 0xb0, v232
	v_lshl_add_u64 v[144:145], v[230:231], 0, v[144:145]
	v_ashrrev_i32_e32 v81, 31, v80
	v_lshlrev_b64 v[144:145], 12, v[80:81]
	v_lshl_add_u64 v[148:149], v[230:231], 0, v[144:145]
	global_load_dwordx4 v[152:155], v[148:149], off offset:16
	global_load_dwordx4 v[156:159], v[148:149], off
	global_load_dwordx4 v[144:147], v[148:149], off offset:528
	s_nop 0
	global_load_dwordx4 v[148:151], v[148:149], off offset:512
	v_lshlrev_b64 v[88:89], 10, v[86:87]
	v_lshl_add_u64 v[90:91], v[88:89], 0, v[228:229]
	s_mov_b64 s[58:59], -1
	s_and_b64 vcc, exec, s[52:53]
	v_lshl_add_u64 v[88:89], v[90:91], 2, s[20:21]
	s_waitcnt vmcnt(24)
	v_pk_add_f32 v[202:203], v[58:59], v[202:203]
	s_waitcnt vmcnt(24)
	v_pk_add_f32 v[206:207], v[62:63], v[206:207]
	v_pk_add_f32 v[204:205], v[60:61], v[204:205]
	v_pk_add_f32 v[200:201], v[56:57], v[200:201]
	s_waitcnt vmcnt(24)
	v_pk_add_f32 v[60:61], v[52:53], v[196:197]
	v_pk_add_f32 v[56:57], v[48:49], v[192:193]
	global_store_dwordx4 v[88:89], v[204:207], off
	global_store_dwordx4 v[88:89], v[200:203], off offset:16
	s_cbranch_vccz .LBB0_93
	v_pk_add_f32 v[62:63], v[54:55], v[198:199]
	v_pk_add_f32 v[58:59], v[50:51], v[194:195]
	global_store_dwordx4 v[88:89], v[60:63], off offset:512
	global_store_dwordx4 v[88:89], v[56:59], off offset:528
	s_mov_b64 s[58:59], 0
.LBB0_93:
	s_andn2_b64 vcc, exec, s[58:59]
	s_cbranch_vccnz .LBB0_97
	v_mul_f32_e32 v48, v205, v205
	v_mul_f32_e32 v49, v207, v207
	v_fmac_f32_e32 v48, v204, v204
	v_fmac_f32_e32 v49, v206, v206
	v_add_f32_e32 v48, v48, v49
	v_mul_f32_e32 v49, v201, v201
	v_mul_f32_e32 v52, v203, v203
	v_fmac_f32_e32 v49, v200, v200
	v_fmac_f32_e32 v52, v202, v202
	v_add_f32_e32 v49, v49, v52
	v_pk_mul_f32 v[62:63], v[76:77], v[200:201]
	v_add_f32_e32 v196, v48, v49
	v_pk_mul_f32 v[48:49], v[74:75], v[206:207]
	v_pk_mul_f32 v[58:59], v[78:79], v[202:203]
	v_cvt_pk_bf16_f32 v202, v62, v63
	v_pk_add_f32 v[62:63], v[54:55], v[198:199]
	v_cvt_pk_bf16_f32 v201, v48, v49
	v_mul_f32_e32 v48, v61, v61
	v_mul_f32_e32 v49, v63, v63
	v_cvt_pk_bf16_f32 v203, v58, v59
	v_pk_add_f32 v[58:59], v[50:51], v[194:195]
	v_fmac_f32_e32 v48, v60, v60
	v_fmac_f32_e32 v49, v62, v62
	v_add_f32_e32 v48, v48, v49
	v_mul_f32_e32 v49, v57, v57
	v_mul_f32_e32 v50, v59, v59
	v_fmac_f32_e32 v49, v56, v56
	v_fmac_f32_e32 v50, v58, v58
	v_add_f32_e32 v49, v49, v50
	v_add_f32_e32 v48, v48, v49
	v_cmp_lt_i32_e32 vcc, v251, v246
	v_pk_mul_f32 v[52:53], v[72:73], v[204:205]
	v_add_f32_e32 v51, v196, v48
	v_cndmask_b32_e32 v48, v245, v251, vcc
	v_cvt_pk_bf16_f32 v200, v52, v53
	v_lshl_add_u64 v[192:193], v[90:91], 1, s[36:37]
	v_lshlrev_b32_e32 v48, 2, v48
	global_store_dwordx4 v[192:193], v[200:203], off
	global_store_dwordx4 v[88:89], v[60:63], off offset:512
	global_store_dwordx4 v[88:89], v[56:59], off offset:528
	v_pk_mul_f32 v[52:53], v[66:67], v[62:63]
	ds_bpermute_b32 v62, v48, v51
	v_pk_mul_f32 v[48:49], v[64:65], v[60:61]
	v_cmp_lt_i32_e32 vcc, v252, v246
	v_cvt_pk_bf16_f32 v50, v48, v49
	v_pk_mul_f32 v[54:55], v[70:71], v[58:59]
	v_cndmask_b32_e32 v49, v245, v252, vcc
	s_waitcnt lgkmcnt(0)
	v_add_f32_e32 v48, v51, v62
	v_lshlrev_b32_e32 v49, 2, v49
	ds_bpermute_b32 v49, v49, v48
	v_pk_mul_f32 v[56:57], v[68:69], v[56:57]
	v_cvt_pk_bf16_f32 v51, v52, v53
	v_cvt_pk_bf16_f32 v52, v56, v57
	v_cvt_pk_bf16_f32 v53, v54, v55
	global_store_dwordx4 v[192:193], v[50:53], off offset:256
	s_and_saveexec_b64 s[58:59], s[4:5]
	s_cbranch_execz .LBB0_96
	v_readlane_b32 s18, v254, 37
	v_lshlrev_b64 v[50:51], 6, v[86:87]
	v_readlane_b32 s19, v254, 38
	s_lshl_b32 s16, s70, 2
	s_waitcnt lgkmcnt(0)
	v_add_f32_e32 v48, v48, v49
	v_lshl_add_u64 v[50:51], s[18:19], 0, v[50:51]
	v_lshl_add_u64 v[50:51], s[56:57], 2, v[50:51]
	v_lshl_add_u64 v[50:51], v[50:51], 0, s[16:17]
	global_store_dword v[50:51], v48, off

; __device__ __forceinline__ u32x4 pack8(const f32x4& v0, const f32x4& v1) { u32x4 w; w.x = cvt_pk_bf16(v0[0], v0[1]); w.y = cvt_pk_bf16(v0[2], v0[3]); w.z = cvt_pk_bf16(v1[0], v1[1]); w.w = cvt_pk_bf16(v1[2], v1[3]); return w; }
;     __device__ __forceinline__ void operator()(const f32x4 (&acc)[2][2][4][2], const Unit& u, int wr, int wc, int fr, int fq) const {
;     ...
;             for (int m = 0; m < 4; ++m) { const int row = row0 + ai * HALF + m * 16; const size_t off = (size_t)row * 1024 + col0; float ss = 0.f;
; #pragma unroll
;                 for (int bj = 0; bj < 2; ++bj) { float* op = out + off + bj * HALF;
;                     const f32x4 x0 = bpre[m][bj][0] + acc[ai][bj][m][0], x1 = bpre[m][bj][1] + acc[ai][bj][m][1];
;                     *(f32x4*)op = x0; *(f32x4*)(op + 4) = x1;
;                     if (XG) { ss += ((x0[0] * x0[0] + x0[1] * x0[1]) + (x0[2] * x0[2] + x0[3] * x0[3])) + ((x1[0] * x1[0] + x1[1] * x1[1]) + (x1[2] * x1[2] + x1[3] * x1[3]));
;                         *(u32x4*)(XG + off + bj * HALF) = pack8(x0 * g0[bj], x1 * g1[bj]); } }
;                 if (XG) { ss += __shfl_xor(ss, 16); ss += __shfl_xor(ss, 32); if (fq == 0) rss[(size_t)row * 16 + u.pn * 4 + wc] = ss; } }
.LBB0_97:
	s_waitcnt lgkmcnt(0)
	v_lshlrev_b64 v[48:49], 10, v[84:85]
	v_lshl_add_u64 v[58:59], v[48:49], 0, v[228:229]
	v_lshl_add_u64 v[56:57], v[58:59], 2, s[20:21]
	s_waitcnt vmcnt(20)
	v_pk_add_f32 v[50:51], v[46:47], v[190:191]
	v_pk_add_f32 v[48:49], v[44:45], v[188:189]
	v_pk_add_f32 v[54:55], v[42:43], v[186:187]
	v_pk_add_f32 v[52:53], v[40:41], v[184:185]
	s_mov_b64 s[58:59], -1
	s_and_b64 vcc, exec, s[52:53]
	s_waitcnt vmcnt(20)
	v_pk_add_f32 v[44:45], v[36:37], v[180:181]
	v_pk_add_f32 v[40:41], v[32:33], v[176:177]
	global_store_dwordx4 v[56:57], v[48:51], off
	global_store_dwordx4 v[56:57], v[52:55], off offset:16
	s_cbranch_vccz .LBB0_99
	v_pk_add_f32 v[46:47], v[38:39], v[182:183]
	v_pk_add_f32 v[42:43], v[34:35], v[178:179]
	global_store_dwordx4 v[56:57], v[44:47], off offset:512
	global_store_dwordx4 v[56:57], v[40:43], off offset:528
	s_mov_b64 s[58:59], 0
.LBB0_99:
	s_andn2_b64 vcc, exec, s[58:59]
	s_cbranch_vccnz .LBB0_103
	v_mul_f32_e32 v32, v49, v49
	v_mul_f32_e32 v33, v51, v51
	v_fmac_f32_e32 v32, v48, v48
	v_fmac_f32_e32 v33, v50, v50
	v_add_f32_e32 v32, v32, v33
	v_mul_f32_e32 v33, v53, v53
	v_mul_f32_e32 v36, v55, v55
	v_fmac_f32_e32 v33, v52, v52
	v_fmac_f32_e32 v36, v54, v54
	v_add_f32_e32 v33, v33, v36
	v_add_f32_e32 v60, v32, v33
	v_pk_mul_f32 v[32:33], v[74:75], v[50:51]
	v_pk_mul_f32 v[36:37], v[72:73], v[48:49]
	v_pk_mul_f32 v[42:43], v[78:79], v[54:55]
	v_pk_mul_f32 v[48:49], v[76:77], v[52:53]
	v_cvt_pk_bf16_f32 v46, v36, v37
	v_cvt_pk_bf16_f32 v47, v32, v33
	v_cvt_pk_bf16_f32 v48, v48, v49
	v_cvt_pk_bf16_f32 v49, v42, v43
	v_lshl_add_u64 v[50:51], v[58:59], 1, s[36:37]
	global_store_dwordx4 v[50:51], v[46:49], off
	v_mul_f32_e32 v32, v45, v45
	v_pk_add_f32 v[42:43], v[34:35], v[178:179]
	v_pk_add_f32 v[46:47], v[38:39], v[182:183]
	v_fmac_f32_e32 v32, v44, v44
	v_mul_f32_e32 v33, v47, v47
	v_fmac_f32_e32 v33, v46, v46
	v_add_f32_e32 v32, v32, v33
	v_mul_f32_e32 v33, v41, v41
	v_mul_f32_e32 v34, v43, v43
	v_fmac_f32_e32 v33, v40, v40
	v_fmac_f32_e32 v34, v42, v42
	v_add_f32_e32 v33, v33, v34
	v_add_f32_e32 v32, v32, v33
	v_cmp_lt_i32_e32 vcc, v251, v246
	v_add_f32_e32 v35, v60, v32
	global_store_dwordx4 v[56:57], v[44:47], off offset:512
	global_store_dwordx4 v[56:57], v[40:43], off offset:528
	v_cndmask_b32_e32 v32, v245, v251, vcc
	v_lshlrev_b32_e32 v32, 2, v32
	v_pk_mul_f32 v[36:37], v[66:67], v[46:47]
	ds_bpermute_b32 v46, v32, v35
	v_pk_mul_f32 v[32:33], v[64:65], v[44:45]
	v_cmp_lt_i32_e32 vcc, v252, v246
	v_cvt_pk_bf16_f32 v34, v32, v33
	v_pk_mul_f32 v[38:39], v[70:71], v[42:43]
	v_cndmask_b32_e32 v33, v245, v252, vcc
	s_waitcnt lgkmcnt(0)
	v_add_f32_e32 v32, v35, v46
	v_lshlrev_b32_e32 v33, 2, v33
	ds_bpermute_b32 v33, v33, v32
	v_pk_mul_f32 v[40:41], v[68:69], v[40:41]
	v_cvt_pk_bf16_f32 v35, v36, v37
	v_cvt_pk_bf16_f32 v36, v40, v41
	v_cvt_pk_bf16_f32 v37, v38, v39
	global_store_dwordx4 v[50:51], v[34:37], off offset:256
	s_and_saveexec_b64 s[58:59], s[4:5]
	s_cbranch_execz .LBB0_102
	v_readlane_b32 s18, v254, 37
	v_lshlrev_b64 v[34:35], 6, v[84:85]
	v_readlane_b32 s19, v254, 38
	s_lshl_b32 s16, s70, 2
	s_waitcnt lgkmcnt(0)
	v_add_f32_e32 v32, v32, v33
	v_lshl_add_u64 v[34:35], s[18:19], 0, v[34:35]
	v_lshl_add_u64 v[34:35], s[56:57], 2, v[34:35]
	v_lshl_add_u64 v[34:35], v[34:35], 0, s[16:17]
	global_store_dword v[34:35], v32, off

; __device__ __forceinline__ u32x4 pack8(const f32x4& v0, const f32x4& v1) { u32x4 w; w.x = cvt_pk_bf16(v0[0], v0[1]); w.y = cvt_pk_bf16(v0[2], v0[3]); w.z = cvt_pk_bf16(v1[0], v1[1]); w.w = cvt_pk_bf16(v1[2], v1[3]); return w; }
;     __device__ __forceinline__ void operator()(const f32x4 (&acc)[2][2][4][2], const Unit& u, int wr, int wc, int fr, int fq) const {
;     ...
;             for (int m = 0; m < 4; ++m) { const int row = row0 + ai * HALF + m * 16; const size_t off = (size_t)row * 1024 + col0; float ss = 0.f;
; #pragma unroll
;                 for (int bj = 0; bj < 2; ++bj) { float* op = out + off + bj * HALF;
;                     const f32x4 x0 = bpre[m][bj][0] + acc[ai][bj][m][0], x1 = bpre[m][bj][1] + acc[ai][bj][m][1];
;                     *(f32x4*)op = x0; *(f32x4*)(op + 4) = x1;
;                     if (XG) { ss += ((x0[0] * x0[0] + x0[1] * x0[1]) + (x0[2] * x0[2] + x0[3] * x0[3])) + ((x1[0] * x1[0] + x1[1] * x1[1]) + (x1[2] * x1[2] + x1[3] * x1[3]));
;                         *(u32x4*)(XG + off + bj * HALF) = pack8(x0 * g0[bj], x1 * g1[bj]); } }
;                 if (XG) { ss += __shfl_xor(ss, 16); ss += __shfl_xor(ss, 32); if (fq == 0) rss[(size_t)row * 16 + u.pn * 4 + wc] = ss; } }
.LBB0_103:
	s_waitcnt lgkmcnt(0)
	v_lshlrev_b64 v[32:33], 10, v[82:83]
	v_lshl_add_u64 v[42:43], v[32:33], 0, v[228:229]
	v_lshl_add_u64 v[40:41], v[42:43], 2, s[20:21]
	s_waitcnt vmcnt(16)
	v_pk_add_f32 v[34:35], v[30:31], v[174:175]
	v_pk_add_f32 v[32:33], v[28:29], v[172:173]
	v_pk_add_f32 v[38:39], v[26:27], v[170:171]
	v_pk_add_f32 v[36:37], v[24:25], v[168:169]
	s_mov_b64 s[58:59], -1
	s_and_b64 vcc, exec, s[52:53]
	s_waitcnt vmcnt(16)
	v_pk_add_f32 v[28:29], v[20:21], v[164:165]
	v_pk_add_f32 v[24:25], v[16:17], v[160:161]
	global_store_dwordx4 v[40:41], v[32:35], off
	global_store_dwordx4 v[40:41], v[36:39], off offset:16
	s_cbranch_vccz .LBB0_105
	v_pk_add_f32 v[30:31], v[22:23], v[166:167]
	v_pk_add_f32 v[26:27], v[18:19], v[162:163]
	global_store_dwordx4 v[40:41], v[28:31], off offset:512
	global_store_dwordx4 v[40:41], v[24:27], off offset:528
	s_mov_b64 s[58:59], 0
.LBB0_105:
	s_andn2_b64 vcc, exec, s[58:59]
	s_cbranch_vccnz .LBB0_109
	v_mul_f32_e32 v16, v33, v33
	v_mul_f32_e32 v17, v35, v35
	v_fmac_f32_e32 v16, v32, v32
	v_fmac_f32_e32 v17, v34, v34
	v_add_f32_e32 v16, v16, v17
	v_mul_f32_e32 v17, v37, v37
	v_mul_f32_e32 v20, v39, v39
	v_fmac_f32_e32 v17, v36, v36
	v_fmac_f32_e32 v20, v38, v38
	v_add_f32_e32 v17, v17, v20
	v_add_f32_e32 v44, v16, v17
	v_pk_mul_f32 v[16:17], v[74:75], v[34:35]
	v_pk_mul_f32 v[20:21], v[72:73], v[32:33]
	v_pk_mul_f32 v[26:27], v[78:79], v[38:39]
	v_pk_mul_f32 v[32:33], v[76:77], v[36:37]
	v_cvt_pk_bf16_f32 v30, v20, v21
	v_cvt_pk_bf16_f32 v31, v16, v17
	v_cvt_pk_bf16_f32 v32, v32, v33
	v_cvt_pk_bf16_f32 v33, v26, v27
	v_lshl_add_u64 v[34:35], v[42:43], 1, s[36:37]
	global_store_dwordx4 v[34:35], v[30:33], off
	v_mul_f32_e32 v16, v29, v29
	v_pk_add_f32 v[26:27], v[18:19], v[162:163]
	v_pk_add_f32 v[30:31], v[22:23], v[166:167]
	v_fmac_f32_e32 v16, v28, v28
	v_mul_f32_e32 v17, v31, v31
	v_fmac_f32_e32 v17, v30, v30
	v_add_f32_e32 v16, v16, v17
	v_mul_f32_e32 v17, v25, v25
	v_mul_f32_e32 v18, v27, v27
	v_fmac_f32_e32 v17, v24, v24
	v_fmac_f32_e32 v18, v26, v26
	v_add_f32_e32 v17, v17, v18
	v_add_f32_e32 v16, v16, v17
	v_cmp_lt_i32_e32 vcc, v251, v246
	v_add_f32_e32 v19, v44, v16
	global_store_dwordx4 v[40:41], v[28:31], off offset:512
	global_store_dwordx4 v[40:41], v[24:27], off offset:528
	v_cndmask_b32_e32 v16, v245, v251, vcc
	v_lshlrev_b32_e32 v16, 2, v16
	v_pk_mul_f32 v[20:21], v[66:67], v[30:31]
	ds_bpermute_b32 v30, v16, v19
	v_pk_mul_f32 v[16:17], v[64:65], v[28:29]
	v_cmp_lt_i32_e32 vcc, v252, v246
	v_cvt_pk_bf16_f32 v18, v16, v17
	v_pk_mul_f32 v[22:23], v[70:71], v[26:27]
	v_cndmask_b32_e32 v17, v245, v252, vcc
	s_waitcnt lgkmcnt(0)
	v_add_f32_e32 v16, v19, v30
	v_lshlrev_b32_e32 v17, 2, v17
	ds_bpermute_b32 v17, v17, v16
	v_pk_mul_f32 v[24:25], v[68:69], v[24:25]
	v_cvt_pk_bf16_f32 v19, v20, v21
	v_cvt_pk_bf16_f32 v20, v24, v25
	v_cvt_pk_bf16_f32 v21, v22, v23
	global_store_dwordx4 v[34:35], v[18:21], off offset:256
	s_and_saveexec_b64 s[58:59], s[4:5]
	s_cbranch_execz .LBB0_108
	v_readlane_b32 s18, v254, 37
	v_lshlrev_b64 v[18:19], 6, v[82:83]
	v_readlane_b32 s19, v254, 38
	s_lshl_b32 s16, s70, 2
	s_waitcnt lgkmcnt(0)
	v_add_f32_e32 v16, v16, v17
	v_lshl_add_u64 v[18:19], s[18:19], 0, v[18:19]
	v_lshl_add_u64 v[18:19], s[56:57], 2, v[18:19]
	v_lshl_add_u64 v[18:19], v[18:19], 0, s[16:17]
	global_store_dword v[18:19], v16, off

; __device__ __forceinline__ u32x4 pack8(const f32x4& v0, const f32x4& v1) { u32x4 w; w.x = cvt_pk_bf16(v0[0], v0[1]); w.y = cvt_pk_bf16(v0[2], v0[3]); w.z = cvt_pk_bf16(v1[0], v1[1]); w.w = cvt_pk_bf16(v1[2], v1[3]); return w; }
;     __device__ __forceinline__ void operator()(const f32x4 (&acc)[2][2][4][2], const Unit& u, int wr, int wc, int fr, int fq) const {
;     ...
;             for (int m = 0; m < 4; ++m) { const int row = row0 + ai * HALF + m * 16; const size_t off = (size_t)row * 1024 + col0; float ss = 0.f;
; #pragma unroll
;                 for (int bj = 0; bj < 2; ++bj) { float* op = out + off + bj * HALF;
;                     const f32x4 x0 = bpre[m][bj][0] + acc[ai][bj][m][0], x1 = bpre[m][bj][1] + acc[ai][bj][m][1];
;                     *(f32x4*)op = x0; *(f32x4*)(op + 4) = x1;
;                     if (XG) { ss += ((x0[0] * x0[0] + x0[1] * x0[1]) + (x0[2] * x0[2] + x0[3] * x0[3])) + ((x1[0] * x1[0] + x1[1] * x1[1]) + (x1[2] * x1[2] + x1[3] * x1[3]));
;                         *(u32x4*)(XG + off + bj * HALF) = pack8(x0 * g0[bj], x1 * g1[bj]); } }
;                 if (XG) { ss += __shfl_xor(ss, 16); ss += __shfl_xor(ss, 32); if (fq == 0) rss[(size_t)row * 16 + u.pn * 4 + wc] = ss; } }
.LBB0_109:
	s_waitcnt lgkmcnt(0)
	v_lshlrev_b64 v[16:17], 10, v[80:81]
	v_lshl_add_u64 v[26:27], v[16:17], 0, v[228:229]
	v_lshl_add_u64 v[24:25], v[26:27], 2, s[20:21]
	s_waitcnt vmcnt(12)
	v_pk_add_f32 v[18:19], v[14:15], v[158:159]
	v_pk_add_f32 v[16:17], v[12:13], v[156:157]
	v_pk_add_f32 v[22:23], v[10:11], v[154:155]
	v_pk_add_f32 v[20:21], v[8:9], v[152:153]
	s_mov_b64 s[58:59], -1
	s_and_b64 vcc, exec, s[52:53]
	s_waitcnt vmcnt(12)
	v_pk_add_f32 v[12:13], v[4:5], v[148:149]
	v_pk_add_f32 v[8:9], v[0:1], v[144:145]
	global_store_dwordx4 v[24:25], v[16:19], off
	global_store_dwordx4 v[24:25], v[20:23], off offset:16
	s_cbranch_vccnz .LBB0_112
	s_andn2_b64 vcc, exec, s[58:59]
	s_cbranch_vccz .LBB0_113

; __device__ __forceinline__ u32x4 pack8(const f32x4& v0, const f32x4& v1) { u32x4 w; w.x = cvt_pk_bf16(v0[0], v0[1]); w.y = cvt_pk_bf16(v0[2], v0[3]); w.z = cvt_pk_bf16(v1[0], v1[1]); w.w = cvt_pk_bf16(v1[2], v1[3]); return w; }
;     __device__ __forceinline__ void operator()(const f32x4 (&acc)[2][2][4][2], const Unit& u, int wr, int wc, int fr, int fq) const {
;     ...
;             for (int m = 0; m < 4; ++m) { const int row = row0 + ai * HALF + m * 16; const size_t off = (size_t)row * 1024 + col0; float ss = 0.f;
; #pragma unroll
;                 for (int bj = 0; bj < 2; ++bj) { float* op = out + off + bj * HALF;
;                     const f32x4 x0 = bpre[m][bj][0] + acc[ai][bj][m][0], x1 = bpre[m][bj][1] + acc[ai][bj][m][1];
;                     *(f32x4*)op = x0; *(f32x4*)(op + 4) = x1;
;                     if (XG) { ss += ((x0[0] * x0[0] + x0[1] * x0[1]) + (x0[2] * x0[2] + x0[3] * x0[3])) + ((x1[0] * x1[0] + x1[1] * x1[1]) + (x1[2] * x1[2] + x1[3] * x1[3]));
;                         *(u32x4*)(XG + off + bj * HALF) = pack8(x0 * g0[bj], x1 * g1[bj]); } }
;                 if (XG) { ss += __shfl_xor(ss, 16); ss += __shfl_xor(ss, 32); if (fq == 0) rss[(size_t)row * 16 + u.pn * 4 + wc] = ss; } }
.LBB0_112:
	v_pk_add_f32 v[14:15], v[6:7], v[150:151]
	v_pk_add_f32 v[10:11], v[2:3], v[146:147]
	global_store_dwordx4 v[24:25], v[12:15], off offset:512
	global_store_dwordx4 v[24:25], v[8:11], off offset:528
	s_cbranch_execnz .LBB0_111
.LBB0_113:
	v_mul_f32_e32 v0, v17, v17
	v_mul_f32_e32 v1, v19, v19
	v_fmac_f32_e32 v0, v16, v16
	v_fmac_f32_e32 v1, v18, v18
	v_add_f32_e32 v0, v0, v1
	v_mul_f32_e32 v1, v21, v21
	v_mul_f32_e32 v4, v23, v23
	v_fmac_f32_e32 v1, v20, v20
	v_fmac_f32_e32 v4, v22, v22
	v_add_f32_e32 v1, v1, v4
	v_add_f32_e32 v28, v0, v1
	v_pk_mul_f32 v[0:1], v[74:75], v[18:19]
	v_pk_mul_f32 v[4:5], v[72:73], v[16:17]
	v_pk_mul_f32 v[10:11], v[78:79], v[22:23]
	v_pk_mul_f32 v[16:17], v[76:77], v[20:21]
	v_cvt_pk_bf16_f32 v14, v4, v5
	v_cvt_pk_bf16_f32 v15, v0, v1
	v_cvt_pk_bf16_f32 v16, v16, v17
	v_cvt_pk_bf16_f32 v17, v10, v11
	v_lshl_add_u64 v[18:19], v[26:27], 1, s[36:37]
	global_store_dwordx4 v[18:19], v[14:17], off
	v_mul_f32_e32 v0, v13, v13
	v_pk_add_f32 v[10:11], v[2:3], v[146:147]
	v_pk_add_f32 v[14:15], v[6:7], v[150:151]
	v_fmac_f32_e32 v0, v12, v12
	v_mul_f32_e32 v1, v15, v15
	v_fmac_f32_e32 v1, v14, v14
	v_add_f32_e32 v0, v0, v1
	v_mul_f32_e32 v1, v9, v9
	v_mul_f32_e32 v2, v11, v11
	v_fmac_f32_e32 v1, v8, v8
	v_fmac_f32_e32 v2, v10, v10
	v_add_f32_e32 v1, v1, v2
	v_add_f32_e32 v0, v0, v1
	v_cmp_lt_i32_e32 vcc, v251, v246
	v_add_f32_e32 v3, v28, v0
	global_store_dwordx4 v[24:25], v[12:15], off offset:512
	global_store_dwordx4 v[24:25], v[8:11], off offset:528
	v_cndmask_b32_e32 v0, v245, v251, vcc
	v_lshlrev_b32_e32 v0, 2, v0
	v_pk_mul_f32 v[4:5], v[66:67], v[14:15]
	ds_bpermute_b32 v14, v0, v3
	v_pk_mul_f32 v[0:1], v[64:65], v[12:13]
	v_cmp_lt_i32_e32 vcc, v252, v246
	v_cvt_pk_bf16_f32 v2, v0, v1
	v_pk_mul_f32 v[6:7], v[70:71], v[10:11]
	v_cndmask_b32_e32 v1, v245, v252, vcc
	s_waitcnt lgkmcnt(0)
	v_add_f32_e32 v0, v3, v14
	v_lshlrev_b32_e32 v1, 2, v1
	ds_bpermute_b32 v1, v1, v0
	v_pk_mul_f32 v[8:9], v[68:69], v[8:9]
	v_cvt_pk_bf16_f32 v3, v4, v5
	v_cvt_pk_bf16_f32 v4, v8, v9
	v_cvt_pk_bf16_f32 v5, v6, v7
	global_store_dwordx4 v[18:19], v[2:5], off offset:256
	s_and_saveexec_b64 s[58:59], s[4:5]
	s_cbranch_execz .LBB0_115
	v_readlane_b32 s18, v254, 37
	v_lshlrev_b64 v[2:3], 6, v[80:81]
	v_readlane_b32 s19, v254, 38
	s_lshl_b32 s16, s70, 2
	s_waitcnt lgkmcnt(0)
	v_add_f32_e32 v0, v0, v1
	v_lshl_add_u64 v[2:3], s[18:19], 0, v[2:3]
	v_lshl_add_u64 v[2:3], s[56:57], 2, v[2:3]
	v_lshl_add_u64 v[2:3], v[2:3], 0, s[16:17]
	global_store_dword v[2:3], v0, off
